# grid barrier: first-arriving workgroup of each XCD issues an asynchronous L2 write-back (pre-flush); on top of v50
# baseline (speedup 1.0000x reference)
; __device__ __forceinline__ unsigned xb_ld(unsigned* p)              { return __hip_atomic_load(p, __ATOMIC_RELAXED, __HIP_MEMORY_SCOPE_AGENT); }
; __device__ __forceinline__ unsigned xb_add(unsigned* p, unsigned v) { return __hip_atomic_fetch_add(p, v, __ATOMIC_RELAXED, __HIP_MEMORY_SCOPE_AGENT); }
; #define XB_SPIN(cond, bar) do { unsigned _sp = 0; while (cond) { __builtin_amdgcn_s_sleep(1); \
;     if ((++_sp & 255u) == 0u) { if (xb_ld(&(bar)[XB_TMO])) break; if (_sp > XB_SPIN_CAP) { atomicAdd(&(bar)[XB_TMO], 1u); break; } } } } while (0)
; __device__ __forceinline__ void xcd_barrier(const XcdBarrier& b) {
;     ...
;         const unsigned old = xb_add(&bar[XB_XSUB(b.x)], 1u);
;         const unsigned gen = old / nloc;
;         if (old + 1u == (gen + 1u) * nloc) {
;             __builtin_amdgcn_fence(__ATOMIC_RELEASE, "agent");
;             asm volatile("s_waitcnt vmcnt(0)" ::: "memory");
;             const unsigned og = xb_add(&bar[XB_TOP], 1u);
;             const unsigned tg = og / nx;
;             if (og + 1u == (tg + 1u) * nx) xb_add(&bar[XB_TOPGEN], 1u);
;             else XB_SPIN(xb_ld(&bar[XB_TOPGEN]) == tg, bar);
;             __builtin_amdgcn_fence(__ATOMIC_ACQUIRE, "agent");
;             xb_add(&bar[XB_XGEN(b.x)], 1u);
;             asm volatile("s_waitcnt vmcnt(0)" ::: "memory");
;         } else {
;             XB_SPIN(xb_ld(&bar[XB_XGEN(b.x)]) == gen, bar);
.LBB0_652:
	global_atomic_add v3, v[164:165], v190, off sc0
	v_cvt_f32_u32_e32 v1, v2
	v_sub_u32_e32 v4, 0, v2
	v_rcp_iflag_f32_e32 v1, v1
	s_nop 0
	v_mul_f32_e32 v1, 0x4f7ffffe, v1
	v_cvt_u32_f32_e32 v1, v1
	v_mul_lo_u32 v4, v4, v1
	v_mul_hi_u32 v4, v1, v4
	v_add_u32_e32 v1, v1, v4
	s_waitcnt vmcnt(0)
	v_mul_hi_u32 v1, v3, v1
	v_mul_lo_u32 v4, v1, v2
	v_sub_u32_e32 v4, v3, v4
	v_add_u32_e32 v5, 1, v1
	v_cmp_ge_u32_e32 vcc, v4, v2
	v_add_u32_e32 v3, 1, v3
	s_nop 0
	v_cndmask_b32_e32 v1, v1, v5, vcc
	v_sub_u32_e32 v5, v4, v2
	v_cndmask_b32_e32 v4, v4, v5, vcc
	v_add_u32_e32 v5, 1, v1
	v_cmp_ge_u32_e32 vcc, v4, v2
	s_nop 1
	v_cndmask_b32_e32 v1, v1, v5, vcc
	v_mul_lo_u32 v4, v2, v1
	v_add_u32_e32 v2, v4, v2
	v_add_u32_e32 v5, 1, v4
	v_cmp_eq_u32_e32 vcc, v3, v5
	s_and_saveexec_b64 s[100:101], vcc
	s_cbranch_execz .Lpf0
	buffer_wbl2 sc1
.Lpf0:
	s_mov_b64 exec, s[100:101]
	v_cmp_ne_u32_e32 vcc, v3, v2
	s_and_saveexec_b64 s[6:7], vcc
	s_xor_b64 s[6:7], exec, s[6:7]
	s_cbranch_execz .LBB0_666
	s_waitcnt lgkmcnt(0)
	global_load_dword v0, v[166:167], off sc1
	s_waitcnt vmcnt(0)
	v_cmp_eq_u32_e32 vcc, v0, v1
	s_and_saveexec_b64 s[12:13], vcc
	s_cbranch_execz .LBB0_665
	s_mov_b32 s8, 1
	s_mov_b64 s[38:39], 0
	s_branch .LBB0_656
